# attention A2+C2b: lut[127] read hoisted out of tile loops, ds_bpermute xor-32 max replaced by v_permlane32_swap
# baseline (speedup 1.0000x reference)
; #define TIDX (tid_launder())
; DI void setup_lut(const Params& p, float* lut) {
;   ((float4*)lut)[TIDX] = ((const float4*)p.lutg)[TIDX];
;   __syncthreads();
; }
; DI void phaseC2b(const Params& p, const float* lut, bool dry) {
;   const int lane = TIDX & 63, wid = TIDX >> 6, r = lane & 31, hh = lane >> 5;
; #pragma unroll 1
;   for (int u = blockIdx.x * 4 + wid; u < 4096; u += gridDim.x * 4) {
;     const int itp = (u >> 11) & 1, kq = (u >> 6) & 31;
;     const int qb = itp ? kq : 63 - kq, b = (u >> 2) & 15, hd = u & 3;
;     const int t = qb * 32 + r;
;     const size_t tok = (size_t)b * SEQ + t;
;     bf16x8 qf[4];
; #pragma unroll
;     for (int ks = 0; ks < 4; ++ks) qf[ks] = ld16(p.projA + tok * LDA_A + 256 + hd * 64 + ks * 16 + hh * 8);
;     const float* lh = lut + (4 + hd) * 128;
;     const unsigned selm = p.selmask[tok];
;     const float gt0 = p.small[tok * 32 + 16 + hd * 3], gt1 = p.small[tok * 32 + 17 + hd * 3], gt2 = p.small[tok * 32 + 18 + hd * 3];
.LBB0_25:
	s_mov_b64 s[2:3], 0
	s_andn2_b64 vcc, exec, s[0:1]
	s_mov_b64 s[0:1], 0
	s_cbranch_vccnz .LBB0_88
	v_mov_b32_e32 v2, v230
	v_readlane_b32 s0, v250, 50
	v_readlane_b32 s2, v250, 52
	v_ashrrev_i32_e32 v3, 31, v2
	v_readlane_b32 s3, v250, 53
	v_mov_b32_e32 v0, v230
	v_readlane_b32 s0, v250, 61
	v_lshl_add_u64 v[2:3], v[2:3], 4, s[2:3]
	global_load_dwordx4 v[2:5], v[2:3], off
	v_lshlrev_b32_e32 v0, 4, v0
	v_readlane_b32 s1, v250, 51
	s_waitcnt vmcnt(0)
	ds_write_b128 v0, v[2:5]
	v_mov_b32_e32 v2, v230
	v_mov_b32_e32 v0, v230
	s_waitcnt lgkmcnt(0)
	s_barrier
	s_nop 0
	v_ashrrev_i32_e32 v3, 6, v0
	v_add_u32_e32 v133, s0, v3
	v_cmp_gt_i32_e32 vcc, s97, v133
	s_mov_b64 s[0:1], exec
	s_mov_b64 s[38:39], s[0:1]
	s_and_b64 s[0:1], s[0:1], vcc
	s_mov_b64 exec, s[0:1]
	s_cbranch_execz .LBB0_84
	v_bfe_u32 v0, v0, 6, 2
	v_readlane_b32 s16, v252, 57
	v_and_b32_e32 v194, 31, v2
	v_lshlrev_b32_e32 v195, 9, v0
	ds_read_b32 v244, v195 offset:2556
	v_mul_u32_u24_e32 v6, 3, v0
	v_lshlrev_b32_e32 v0, 7, v0
	v_readlane_b32 s24, v253, 1
	v_readlane_b32 s25, v253, 2
	v_lshrrev_b32_e32 v2, 1, v2
	v_and_b32_e32 v2, 16, v2
	v_lshl_add_u64 v[4:5], s[24:25], 0, v[0:1]
	v_mov_b32_e32 v3, v1
	v_readlane_b32 s28, v253, 5
	v_readlane_b32 s29, v253, 6
	v_readlane_b32 s30, v253, 7
	v_readlane_b32 s31, v253, 8
	v_lshl_add_u64 v[134:135], v[4:5], 0, v[2:3]
	v_lshlrev_b32_e32 v2, 2, v6
	v_lshl_add_u64 v[136:137], s[30:31], 0, v[2:3]
	v_lshl_add_u64 v[138:139], s[28:29], 0, v[0:1]
	s_mov_b64 s[68:69], 0
	v_readlane_b32 s17, v252, 58
	v_readlane_b32 s18, v252, 59
	v_readlane_b32 s19, v252, 60
	v_readlane_b32 s20, v252, 61
	v_readlane_b32 s21, v252, 62
	v_readlane_b32 s22, v252, 63
	v_readlane_b32 s23, v253, 0
	v_readlane_b32 s26, v253, 3
	v_readlane_b32 s27, v253, 4
	s_branch .LBB0_29

; template <int MODE> ...
;     ...
;     tmax = fmaxf(tmax, __shfl_xor(tmax, 32));
;     const float m_new = fmaxf(m_run, tmax);
;     if (__ballot(m_new != m_run) != 0ull) {
;       const float alpha = __builtin_amdgcn_exp2f(m_run - m_new);
;       l_run *= alpha; m_run = m_new;
; #pragma unroll
;       for (int e = 0; e < 16; ++e) { oacc[0][e] *= alpha; oacc[1][e] *= alpha; }
;     }
.LBB0_34:
	s_or_b64 exec, exec, s[34:35]
	v_mov_b32_e32 v34, v224
	v_mov_b32_e32 v246, v224
	s_nop 1
	v_permlane32_swap_b32_e32 v34, v246
	v_max3_f32 v34, v122, v34, v246
	v_cmp_neq_f32_e32 vcc, v34, v122
	s_cbranch_vccz .LBB0_41
	v_sub_f32_e32 v35, v122, v34
	v_exp_f32_e32 v36, v35
	v_mov_b32_e32 v122, v34
	v_mul_f32_e32 v189, v189, v36
	v_pk_mul_f32 v[32:33], v[32:33], v[36:37] op_sel_hi:[1,0]
	v_pk_mul_f32 v[30:31], v[30:31], v[36:37] op_sel_hi:[1,0]
	v_pk_mul_f32 v[28:29], v[28:29], v[36:37] op_sel_hi:[1,0]
	v_pk_mul_f32 v[26:27], v[26:27], v[36:37] op_sel_hi:[1,0]
	v_pk_mul_f32 v[24:25], v[24:25], v[36:37] op_sel_hi:[1,0]
	v_pk_mul_f32 v[22:23], v[22:23], v[36:37] op_sel_hi:[1,0]
	v_pk_mul_f32 v[20:21], v[20:21], v[36:37] op_sel_hi:[1,0]
	v_pk_mul_f32 v[18:19], v[18:19], v[36:37] op_sel_hi:[1,0]
	v_pk_mul_f32 v[16:17], v[16:17], v[36:37] op_sel_hi:[1,0]
	v_pk_mul_f32 v[14:15], v[14:15], v[36:37] op_sel_hi:[1,0]
	v_pk_mul_f32 v[12:13], v[12:13], v[36:37] op_sel_hi:[1,0]
	v_pk_mul_f32 v[10:11], v[10:11], v[36:37] op_sel_hi:[1,0]
	v_pk_mul_f32 v[8:9], v[8:9], v[36:37] op_sel_hi:[1,0]
	v_pk_mul_f32 v[6:7], v[6:7], v[36:37] op_sel_hi:[1,0]
	v_pk_mul_f32 v[4:5], v[4:5], v[36:37] op_sel_hi:[1,0]
	v_pk_mul_f32 v[2:3], v[2:3], v[36:37] op_sel_hi:[1,0]

; template <int MODE> ...
;     ...
;     if (far) {
;       const float b127 = lut[127];
;       const unsigned mbs = mb >> (4 * hh);
;       const int dbase = t - key0 - 4 * hh;
; #pragma unroll
;       for (int e = 0; e < 16; ++e) {
;         const int ce = (e & 3) + 8 * (e >> 2);
;         bool ok;
;         if (MODE == 0) ok = (mbs & (1u << ce)) != 0u;
;         else if (MODE == 1) ok = mb != 0u;
;         else ok = (dbase - ce) < 512;
;         const float lg = __builtin_fmaf(s[e], 0.18033688011112042f, b127);
;         pv[e] = ok ? lg : -1e30f;
;         tmax = fmaxf(tmax, pv[e]);
;       }
.LBB0_39:
	s_andn2_saveexec_b64 s[34:35], s[34:35]
	s_cbranch_execz .LBB0_34
	v_cmp_gt_i32_e32 vcc, s77, v223
	s_waitcnt lgkmcnt(0)
	v_pk_fma_f32 v[34:35], v[34:35], s[96:97], v[244:245] op_sel_hi:[1,0,0]
	s_nop 0
	v_cndmask_b32_e32 v123, v235, v35, vcc
	v_cmp_gt_i32_e32 vcc, s77, v222
	v_pk_fma_f32 v[36:37], v[36:37], s[96:97], v[244:245] op_sel_hi:[1,0,0]
	s_nop 0
	v_cndmask_b32_e32 v124, v235, v34, vcc
	v_cmp_gt_i32_e32 vcc, s77, v221
	v_max3_f32 v34, v124, s82, v123
	s_nop 0
	v_cndmask_b32_e32 v125, v235, v37, vcc
	v_cmp_gt_i32_e32 vcc, s77, v220
	s_nop 1
	v_cndmask_b32_e32 v126, v235, v36, vcc
	v_max3_f32 v36, v34, v126, v125
	v_pk_fma_f32 v[34:35], v[38:39], s[96:97], v[244:245] op_sel_hi:[1,0,0]
	v_cmp_gt_i32_e32 vcc, s77, v219
	s_nop 1
	v_cndmask_b32_e32 v127, v235, v35, vcc
	v_cmp_gt_i32_e32 vcc, s77, v218
	s_nop 1
	v_cndmask_b32_e32 v128, v235, v34, vcc
	v_pk_fma_f32 v[34:35], v[40:41], s[96:97], v[244:245] op_sel_hi:[1,0,0]
	v_cmp_gt_i32_e32 vcc, s77, v217
	v_max3_f32 v36, v36, v128, v127
	s_nop 0
	v_cndmask_b32_e32 v129, v235, v35, vcc
	v_cmp_gt_i32_e32 vcc, s77, v216
	s_nop 1
	v_cndmask_b32_e32 v188, v235, v34, vcc
	v_pk_fma_f32 v[34:35], v[42:43], s[96:97], v[244:245] op_sel_hi:[1,0,0]
	v_cmp_gt_i32_e32 vcc, s77, v208
	v_max3_f32 v36, v36, v188, v129
	s_nop 0
	v_cndmask_b32_e32 v207, v235, v35, vcc
	v_cmp_gt_i32_e32 vcc, s77, v206
	s_nop 1
	v_cndmask_b32_e32 v209, v235, v34, vcc
	v_pk_fma_f32 v[34:35], v[44:45], s[96:97], v[244:245] op_sel_hi:[1,0,0]
	v_cmp_gt_i32_e32 vcc, s77, v205
	v_max3_f32 v36, v36, v209, v207
	s_nop 0
	v_cndmask_b32_e32 v211, v235, v35, vcc
	v_cmp_gt_i32_e32 vcc, s77, v204
	s_nop 1
	v_cndmask_b32_e32 v212, v235, v34, vcc
	v_pk_fma_f32 v[34:35], v[46:47], s[96:97], v[244:245] op_sel_hi:[1,0,0]
	v_cmp_gt_i32_e32 vcc, s77, v193
	v_max3_f32 v36, v36, v212, v211
	s_nop 0
	v_cndmask_b32_e32 v213, v235, v35, vcc
	v_cmp_gt_i32_e32 vcc, s77, v192
	s_nop 1
	v_cndmask_b32_e32 v214, v235, v34, vcc
	v_pk_fma_f32 v[34:35], v[48:49], s[96:97], v[244:245] op_sel_hi:[1,0,0]
	v_cmp_gt_i32_e32 vcc, s77, v191
	v_max3_f32 v36, v36, v214, v213
	s_nop 0
	v_cndmask_b32_e32 v210, v235, v35, vcc
	v_cmp_gt_i32_e32 vcc, s77, v190
	s_nop 1
	v_cndmask_b32_e32 v215, v235, v34, vcc
	v_max3_f32 v224, v36, v215, v210
	s_branch .LBB0_34

; #define MFMA32(a, b, c) __builtin_amdgcn_mfma_f32_32x32x16_bf16((a), (b), (c), 0, 0, 0)
; DI int crow(int reg, int hh) { return (reg & 3) + 8 * (reg >> 2) + 4 * hh; }
; template <int MODE> ...
;     ...
;     int kn = kt + 1;
;     if (MODE == 1) { while (kn < kt_end && !((orm >> (kn >> 1)) & 1u)) ++kn; }
;     const int kl = kn < kt_end ? kn : kt;
;     A_LOAD(n_, kl);
;     const int key0 = kt * 32;
;     unsigned mb = c_mb;
;     if (MODE == 1) mb = ((selm >> (key0 >> 6)) & 1u) ? 0xffffffffu : 0u;
;     f32x16 s;
; #pragma unroll
;     for (int e = 0; e < 16; ++e) s[e] = 0.f;
;     s = MFMA32(c_k0, qf[0], s); s = MFMA32(c_k1, qf[1], s); s = MFMA32(c_k2, qf[2], s); s = MFMA32(c_k3, qf[3], s);
;     float tmax = -1e30f;
;     f32x16 pv;
;     const int q0u = __builtin_amdgcn_readfirstlane(t - r);
;     const bool far = (MODE != 3) && (q0u - (key0 + 31) >= 127);
;     if (far) {
;       const float b127 = lut[127];
;       const unsigned mbs = mb >> (4 * hh);
;       const int dbase = t - key0 - 4 * hh;
; #pragma unroll
;       for (int e = 0; e < 16; ++e) {
;         const int ce = (e & 3) + 8 * (e >> 2);
;         bool ok;
;         if (MODE == 0) ok = (mbs & (1u << ce)) != 0u;
;         else if (MODE == 1) ok = mb != 0u;
;         else ok = (dbase - ce) < 512;
;         const float lg = __builtin_fmaf(s[e], 0.18033688011112042f, b127);
;         pv[e] = ok ? lg : -1e30f;
;         tmax = fmaxf(tmax, pv[e]);
;       }
;     } else {
; #pragma unroll
;       for (int e = 0; e < 16; ++e) {
;         const int kk = crow(e, hh), kidx = key0 + kk;
;         const int pos = MODE == 3 ? 16 * kidx + 31 : kidx;
;         const int dist = t - pos;
;         bool ok = dist >= 0 && ((mb >> kk) & 1u);
;         if (MODE == 2) ok = ok && dist < 512;
;         if (MODE == 3) ok = ok && kidx < 127;
;         int di = dist < 0 ? 0 : (dist > 127 ? 127 : dist);
;         const float lg = __builtin_fmaf(s[e], 0.18033688011112042f, lut[di]);
;         pv[e] = ok ? lg : -1e30f;
;         tmax = fmaxf(tmax, pv[e]);
;       }
;     }
;     tmax = fmaxf(tmax, __shfl_xor(tmax, 32));
;     const float m_new = fmaxf(m_run, tmax);
;     if (__ballot(m_new != m_run) != 0ull) {
.LBB0_60:
	s_waitcnt vmcnt(7)
	v_mfma_f32_32x32x16_bf16 v[34:49], v[50:53], v[66:69], 0
	s_waitcnt vmcnt(6)
	v_mov_b64_e32 v[100:101], v[56:57]
	v_mov_b64_e32 v[98:99], v[54:55]
	s_waitcnt vmcnt(5)
	v_mov_b64_e32 v[128:129], v[60:61]
	v_mov_b64_e32 v[126:127], v[58:59]
	s_waitcnt vmcnt(4)
	v_mov_b64_e32 v[124:125], v[64:65]
	s_cmpk_lg_i32 s8, 0xfa00
	v_mov_b64_e32 v[122:123], v[62:63]
	v_mfma_f32_32x32x16_bf16 v[34:49], v[98:101], v[70:73], v[34:49]
	s_cselect_b32 s14, s9, 0x1800
	s_lshl_b64 s[2:3], s[14:15], 1
	v_lshl_add_u64 v[62:63], v[114:115], 0, s[2:3]
	v_lshl_add_u64 v[110:111], v[116:117], 0, s[2:3]
	global_load_dwordx4 v[50:53], v[62:63], off
	global_load_dwordx4 v[54:57], v[62:63], off offset:1024
	global_load_dwordx4 v[58:61], v[62:63], off offset:2048
	s_nop 0
	global_load_dwordx4 v[62:65], v[62:63], off offset:3072
	s_nop 0
	global_load_dwordx4 v[98:101], v[110:111], off
	global_load_dwordx4 v[102:105], v[110:111], off offset:1024
	global_load_dwordx4 v[106:109], v[110:111], off offset:2048
	s_nop 0
	global_load_dwordx4 v[110:113], v[110:111], off offset:3072
	v_add_u32_e32 v121, s8, v119
	v_mfma_f32_32x32x16_bf16 v[34:49], v[126:129], v[74:77], v[34:49]
	v_subrev_u32_e32 v0, 31, v121
	v_cmp_lt_i32_e32 vcc, -1, v0
	v_med3_i32 v0, v0, 0, v234
	v_subrev_u32_e32 v126, 47, v121
	v_subrev_u32_e32 v127, 63, v121
	v_lshl_add_u32 v0, v0, 2, v195
	v_cmp_lt_i32_e64 s[2:3], -1, v126
	v_mfma_f32_32x32x16_bf16 v[34:49], v[122:125], v[78:81], v[34:49]
	v_med3_i32 v126, v126, 0, v234
	v_med3_i32 v128, v127, 0, v234
	ds_read_b32 v0, v0 offset:2048
	v_lshl_add_u32 v126, v126, 2, v195
	v_lshl_add_u32 v128, v128, 2, v195
	ds_read_b32 v126, v126 offset:2048
	ds_read_b32 v128, v128 offset:2048
	v_add_u32_e32 v123, 0xffffff61, v121
	v_med3_i32 v124, v123, 0, v234
	v_lshl_add_u32 v124, v124, 2, v195
	ds_read_b32 v124, v124 offset:2048
	s_waitcnt lgkmcnt(3)
	v_fmac_f32_e32 v0, 0x3e38aa3b, v34
	s_waitcnt lgkmcnt(2)
	v_fmac_f32_e32 v126, 0x3e38aa3b, v35
	v_cndmask_b32_e32 v35, v235, v0, vcc
	v_cmp_lt_i32_e32 vcc, -1, v127
	s_waitcnt lgkmcnt(1)
	v_fmac_f32_e32 v128, 0x3e38aa3b, v36
	v_add_u32_e32 v36, 0xffffffb1, v121
	v_cndmask_b32_e32 v34, v235, v128, vcc
	v_cmp_lt_i32_e32 vcc, -1, v36
	v_med3_i32 v36, v36, 0, v234
	v_lshl_add_u32 v36, v36, 2, v195
	ds_read_b32 v36, v36 offset:2048
	s_waitcnt lgkmcnt(1)
	v_fmac_f32_e32 v124, 0x3e38aa3b, v38
	v_add_u32_e32 v38, 0xffffff51, v121
	v_cndmask_b32_e64 v0, v235, v126, s[2:3]
	v_max3_f32 v122, v35, s82, v0
	s_waitcnt lgkmcnt(0)
	v_fmac_f32_e32 v36, 0x3e38aa3b, v37
	v_cndmask_b32_e32 v36, v235, v36, vcc
	v_cmp_lt_i32_e32 vcc, -1, v123
	v_add_u32_e32 v123, 0xffffff41, v121
	v_max3_f32 v122, v122, v34, v36
	v_cndmask_b32_e32 v37, v235, v124, vcc
	v_cmp_lt_i32_e32 vcc, -1, v38
	v_med3_i32 v38, v38, 0, v234
	v_lshl_add_u32 v38, v38, 2, v195
	v_med3_i32 v124, v123, 0, v234
	ds_read_b32 v38, v38 offset:2048
	v_lshl_add_u32 v124, v124, 2, v195
	ds_read_b32 v124, v124 offset:2048
	v_cmp_gt_u32_e64 s[2:3], s33, v118
	s_waitcnt lgkmcnt(1)
	v_fmac_f32_e32 v38, 0x3e38aa3b, v39
	v_cndmask_b32_e32 v38, v235, v38, vcc
	v_cmp_lt_i32_e32 vcc, -1, v123
	s_waitcnt lgkmcnt(0)
	v_fmac_f32_e32 v124, 0x3e38aa3b, v40
	v_add_u32_e32 v40, 0xffffff31, v121
	v_cndmask_b32_e32 v39, v235, v124, vcc
	v_cmp_lt_i32_e32 vcc, -1, v40
	v_med3_i32 v40, v40, 0, v234
	v_add_u32_e32 v123, 0xfffffee1, v121
	v_lshl_add_u32 v40, v40, 2, v195
	v_med3_i32 v124, v123, 0, v234
	ds_read_b32 v40, v40 offset:2048
	v_lshl_add_u32 v124, v124, 2, v195
	ds_read_b32 v124, v124 offset:2048
	v_max3_f32 v122, v122, v37, v38
	s_waitcnt lgkmcnt(1)
	v_fmac_f32_e32 v40, 0x3e38aa3b, v41
	v_cndmask_b32_e32 v40, v235, v40, vcc
	v_cmp_lt_i32_e32 vcc, -1, v123
	s_waitcnt lgkmcnt(0)
	v_fmac_f32_e32 v124, 0x3e38aa3b, v42
	v_add_u32_e32 v42, 0xfffffed1, v121
	v_cndmask_b32_e32 v41, v235, v124, vcc
	v_cmp_lt_i32_e32 vcc, -1, v42
	v_med3_i32 v42, v42, 0, v234
	v_add_u32_e32 v123, 0xfffffec1, v121
	v_lshl_add_u32 v42, v42, 2, v195
	v_med3_i32 v124, v123, 0, v234
	ds_read_b32 v42, v42 offset:2048
	v_lshl_add_u32 v124, v124, 2, v195
	ds_read_b32 v124, v124 offset:2048
	v_max3_f32 v122, v122, v39, v40
	s_waitcnt lgkmcnt(1)
	v_fmac_f32_e32 v42, 0x3e38aa3b, v43
	v_cndmask_b32_e32 v42, v235, v42, vcc
	v_cmp_lt_i32_e32 vcc, -1, v123
	s_waitcnt lgkmcnt(0)
	v_fmac_f32_e32 v124, 0x3e38aa3b, v44
	v_add_u32_e32 v44, 0xfffffeb1, v121
	v_cndmask_b32_e32 v43, v235, v124, vcc
	v_cmp_lt_i32_e32 vcc, -1, v44
	v_med3_i32 v44, v44, 0, v234
	v_add_u32_e32 v123, 0xfffffe61, v121
	v_lshl_add_u32 v44, v44, 2, v195
	v_med3_i32 v124, v123, 0, v234
	ds_read_b32 v44, v44 offset:2048
	v_lshl_add_u32 v124, v124, 2, v195
	ds_read_b32 v124, v124 offset:2048
	v_max3_f32 v122, v122, v41, v42
	s_waitcnt lgkmcnt(1)
	v_fmac_f32_e32 v44, 0x3e38aa3b, v45
	v_cndmask_b32_e32 v44, v235, v44, vcc
	v_cmp_lt_i32_e32 vcc, -1, v123
	s_waitcnt lgkmcnt(0)
	v_fmac_f32_e32 v124, 0x3e38aa3b, v46
	v_add_u32_e32 v46, 0xfffffe51, v121
	v_add_u32_e32 v123, 0xfffffe41, v121
	v_cndmask_b32_e32 v45, v235, v124, vcc
	v_cmp_lt_i32_e32 vcc, -1, v46
	v_med3_i32 v46, v46, 0, v234
	v_med3_i32 v124, v123, 0, v234
	v_lshl_add_u32 v46, v46, 2, v195
	v_lshl_add_u32 v124, v124, 2, v195
	ds_read_b32 v46, v46 offset:2048
	ds_read_b32 v124, v124 offset:2048
	v_max3_f32 v122, v122, v43, v44
	s_waitcnt lgkmcnt(1)
	v_fmac_f32_e32 v46, 0x3e38aa3b, v47
	s_waitcnt lgkmcnt(0)
	v_fmac_f32_e32 v124, 0x3e38aa3b, v48
	v_add_u32_e32 v48, 0xfffffe31, v121
	v_med3_i32 v121, v48, 0, v234
	v_cndmask_b32_e32 v46, v235, v46, vcc
	v_lshl_add_u32 v121, v121, 2, v195
	v_max3_f32 v47, v122, v45, v46
	ds_read_b32 v122, v121 offset:2048
	v_cmp_lt_i32_e32 vcc, -1, v123
	s_waitcnt lgkmcnt(0)
	v_fmac_f32_e32 v122, 0x3e38aa3b, v49
	v_cndmask_b32_e32 v121, v235, v124, vcc
	v_cmp_lt_i32_e32 vcc, -1, v48
	s_and_b64 vcc, s[2:3], vcc
	s_nop 0
	v_cndmask_b32_e32 v48, v235, v122, vcc
	v_max3_f32 v47, v47, v121, v48
	v_mov_b32_e32 v49, v47
	v_mov_b32_e32 v246, v47
	s_nop 1
	v_permlane32_swap_b32_e32 v49, v246
	v_max3_f32 v47, v120, v49, v246
	v_cmp_neq_f32_e32 vcc, v47, v120
	s_cbranch_vccz .LBB0_62
; template <int MODE> ...
;     ...
;     if (__ballot(m_new != m_run) != 0ull) {
;       const float alpha = __builtin_amdgcn_exp2f(m_run - m_new);
;       l_run *= alpha; m_run = m_new;
; #pragma unroll
;       for (int e = 0; e < 16; ++e) { oacc[0][e] *= alpha; oacc[1][e] *= alpha; }
;     }
	v_sub_f32_e32 v49, v120, v47
	v_exp_f32_e32 v120, v49
	s_nop 0
	v_mul_f32_e32 v189, v189, v120
	v_pk_mul_f32 v[32:33], v[32:33], v[120:121] op_sel_hi:[1,0]
	v_pk_mul_f32 v[30:31], v[30:31], v[120:121] op_sel_hi:[1,0]
	v_pk_mul_f32 v[28:29], v[28:29], v[120:121] op_sel_hi:[1,0]
	v_pk_mul_f32 v[26:27], v[26:27], v[120:121] op_sel_hi:[1,0]
	v_pk_mul_f32 v[24:25], v[24:25], v[120:121] op_sel_hi:[1,0]
	v_pk_mul_f32 v[22:23], v[22:23], v[120:121] op_sel_hi:[1,0]
	v_pk_mul_f32 v[20:21], v[20:21], v[120:121] op_sel_hi:[1,0]
	v_pk_mul_f32 v[18:19], v[18:19], v[120:121] op_sel_hi:[1,0]
	v_pk_mul_f32 v[16:17], v[16:17], v[120:121] op_sel_hi:[1,0]
	v_pk_mul_f32 v[14:15], v[14:15], v[120:121] op_sel_hi:[1,0]
	v_pk_mul_f32 v[12:13], v[12:13], v[120:121] op_sel_hi:[1,0]
	v_pk_mul_f32 v[10:11], v[10:11], v[120:121] op_sel_hi:[1,0]
	v_pk_mul_f32 v[8:9], v[8:9], v[120:121] op_sel_hi:[1,0]
	v_pk_mul_f32 v[6:7], v[6:7], v[120:121] op_sel_hi:[1,0]
	v_pk_mul_f32 v[4:5], v[4:5], v[120:121] op_sel_hi:[1,0]
	v_pk_mul_f32 v[2:3], v[2:3], v[120:121] op_sel_hi:[1,0]
	s_branch .LBB0_63

; template <int MODE> ...
;     ...
;     tmax = fmaxf(tmax, __shfl_xor(tmax, 32));
;     const float m_new = fmaxf(m_run, tmax);
;     if (__ballot(m_new != m_run) != 0ull) {
;       const float alpha = __builtin_amdgcn_exp2f(m_run - m_new);
;       l_run *= alpha; m_run = m_new;
; #pragma unroll
;       for (int e = 0; e < 16; ++e) { oacc[0][e] *= alpha; oacc[1][e] *= alpha; }
;     }
.LBB0_69:
	s_or_b64 exec, exec, s[2:3]
	v_mov_b32_e32 v0, v207
	v_mov_b32_e32 v246, v207
	s_nop 1
	v_permlane32_swap_b32_e32 v0, v246
	v_max3_f32 v0, v206, v0, v246
	v_cmp_neq_f32_e32 vcc, v0, v206
	s_cbranch_vccz .LBB0_80
	v_sub_f32_e32 v50, v206, v0
	v_exp_f32_e32 v50, v50
	v_mov_b32_e32 v206, v0
	v_mul_f32_e32 v189, v189, v50
	v_pk_mul_f32 v[32:33], v[32:33], v[50:51] op_sel_hi:[1,0]
	v_pk_mul_f32 v[30:31], v[30:31], v[50:51] op_sel_hi:[1,0]
	v_pk_mul_f32 v[28:29], v[28:29], v[50:51] op_sel_hi:[1,0]
	v_pk_mul_f32 v[26:27], v[26:27], v[50:51] op_sel_hi:[1,0]
	v_pk_mul_f32 v[24:25], v[24:25], v[50:51] op_sel_hi:[1,0]
	v_pk_mul_f32 v[22:23], v[22:23], v[50:51] op_sel_hi:[1,0]
	v_pk_mul_f32 v[20:21], v[20:21], v[50:51] op_sel_hi:[1,0]
	v_pk_mul_f32 v[18:19], v[18:19], v[50:51] op_sel_hi:[1,0]
	v_pk_mul_f32 v[16:17], v[16:17], v[50:51] op_sel_hi:[1,0]
	v_pk_mul_f32 v[14:15], v[14:15], v[50:51] op_sel_hi:[1,0]
	v_pk_mul_f32 v[12:13], v[12:13], v[50:51] op_sel_hi:[1,0]
	v_pk_mul_f32 v[10:11], v[10:11], v[50:51] op_sel_hi:[1,0]
	v_pk_mul_f32 v[8:9], v[8:9], v[50:51] op_sel_hi:[1,0]
	v_pk_mul_f32 v[6:7], v[6:7], v[50:51] op_sel_hi:[1,0]
	v_pk_mul_f32 v[4:5], v[4:5], v[50:51] op_sel_hi:[1,0]
	v_pk_mul_f32 v[2:3], v[2:3], v[50:51] op_sel_hi:[1,0]

; template <int MODE> ...
;     ...
;     if (far) {
;       const float b127 = lut[127];
;       const unsigned mbs = mb >> (4 * hh);
;       const int dbase = t - key0 - 4 * hh;
; #pragma unroll
;       for (int e = 0; e < 16; ++e) {
;         const int ce = (e & 3) + 8 * (e >> 2);
;         bool ok;
;         if (MODE == 0) ok = (mbs & (1u << ce)) != 0u;
;         else if (MODE == 1) ok = mb != 0u;
;         else ok = (dbase - ce) < 512;
;         const float lg = __builtin_fmaf(s[e], 0.18033688011112042f, b127);
;         pv[e] = ok ? lg : -1e30f;
;         tmax = fmaxf(tmax, pv[e]);
;       }
.LBB0_78:
	s_andn2_saveexec_b64 s[2:3], s[74:75]
	s_cbranch_execz .LBB0_69
	s_waitcnt lgkmcnt(0)
	s_nop 1
	v_fmamk_f32 v34, v50, 0x3e38aa3b, v244
	v_fmamk_f32 v35, v51, 0x3e38aa3b, v244
	v_fmamk_f32 v36, v52, 0x3e38aa3b, v244
	v_cndmask_b32_e32 v34, v235, v34, vcc
	v_cndmask_b32_e32 v35, v235, v35, vcc
	v_fmamk_f32 v37, v53, 0x3e38aa3b, v244
	v_cndmask_b32_e32 v36, v235, v36, vcc
	v_max3_f32 v38, v34, s82, v35
	v_cndmask_b32_e32 v37, v235, v37, vcc
	v_max3_f32 v40, v38, v36, v37
	v_fmamk_f32 v38, v54, 0x3e38aa3b, v244
	v_fmamk_f32 v39, v55, 0x3e38aa3b, v244
	v_cndmask_b32_e32 v38, v235, v38, vcc
	v_cndmask_b32_e32 v39, v235, v39, vcc
	v_max3_f32 v42, v40, v38, v39
	v_fmamk_f32 v40, v56, 0x3e38aa3b, v244
	v_fmamk_f32 v41, v57, 0x3e38aa3b, v244
	v_cndmask_b32_e32 v40, v235, v40, vcc
	v_cndmask_b32_e32 v41, v235, v41, vcc
	v_max3_f32 v44, v42, v40, v41
	v_fmamk_f32 v42, v58, 0x3e38aa3b, v244
	v_fmamk_f32 v43, v59, 0x3e38aa3b, v244
	v_cndmask_b32_e32 v42, v235, v42, vcc
	v_cndmask_b32_e32 v43, v235, v43, vcc
	v_max3_f32 v46, v44, v42, v43
	v_fmamk_f32 v44, v60, 0x3e38aa3b, v244
	v_fmamk_f32 v45, v61, 0x3e38aa3b, v244
	v_cndmask_b32_e32 v44, v235, v44, vcc
	v_cndmask_b32_e32 v45, v235, v45, vcc
	v_max3_f32 v48, v46, v44, v45
	v_fmamk_f32 v46, v62, 0x3e38aa3b, v244
	v_fmamk_f32 v47, v63, 0x3e38aa3b, v244
	v_cndmask_b32_e32 v46, v235, v46, vcc
	v_cndmask_b32_e32 v47, v235, v47, vcc
	v_max3_f32 v50, v48, v46, v47
	v_fmamk_f32 v48, v64, 0x3e38aa3b, v244
	v_fmamk_f32 v0, v65, 0x3e38aa3b, v244
	v_cndmask_b32_e32 v48, v235, v48, vcc
	v_cndmask_b32_e32 v49, v235, v0, vcc
	v_max3_f32 v207, v50, v48, v49
	s_branch .LBB0_69

; #define TIDX (tid_launder())
; template <int MODE> ...
;     ...
;       const float b127 = lut[127];
; DI void phaseA2(const Params& p, const float* lut, bool dry) {
;   const int lane = TIDX & 63, wid = TIDX >> 6, r = lane & 31, hh = lane >> 5;
; #pragma unroll 1
;   for (int u = blockIdx.x * 4 + wid; u < 4096; u += gridDim.x * 4) {
;     const int itp = (u >> 11) & 1, kq = (u >> 6) & 31;
;     const int qb = kq < 16 ? (itp ? 32 + kq : 63 - kq) : (itp ? kq - 16 : 47 - kq), b = (u >> 2) & 15, hd = u & 3;
;     const int t = qb * 32 + r;
;     const size_t tok = (size_t)b * SEQ + t;
;     bf16x8 qf[4];
; #pragma unroll
;     for (int ks = 0; ks < 4; ++ks) qf[ks] = ld16(p.projA + tok * LDA_A + hd * 64 + ks * 16 + hh * 8);
;     f32x16 oacc[2];
; #pragma unroll
;     for (int e = 0; e < 16; ++e) { oacc[0][e] = 0.f; oacc[1][e] = 0.f; }
;     float m_run = -1e30f, l_run = 0.f;
;     attn_branch<0>(oacc, m_run, l_run, qf, p.akv + ((size_t)b * 4 + hd) * 64 * 2048,
;                    p.avT + ((size_t)b * 4 + hd) * 64 * 2048, 0, qb + 1, t, lut + hd * 128, p.bm + tok * 64, 0u);
.LBB0_315:
	s_or_b64 exec, exec, s[12:13]
	v_mov_b32_e32 v2, v230
	s_waitcnt lgkmcnt(0)
	v_mov_b32_e32 v0, v230
	v_readlane_b32 s0, v250, 61
	v_ashrrev_i32_e32 v3, 6, v0
	s_nop 0
	v_add_u32_e32 v126, s0, v3
	v_cmp_gt_i32_e32 vcc, s97, v126
	s_and_saveexec_b64 s[2:3], vcc
	s_cbranch_execz .LBB0_331
	v_bfe_u32 v6, v0, 6, 2
	v_readlane_b32 s16, v252, 57
	v_and_b32_e32 v127, 31, v2
	v_lshlrev_b32_e32 v0, 7, v6
	v_readlane_b32 s24, v253, 1
	v_readlane_b32 s25, v253, 2
	v_lshrrev_b32_e32 v2, 1, v2
	v_and_b32_e32 v2, 16, v2
	v_lshl_add_u64 v[4:5], s[24:25], 0, v[0:1]
	v_mov_b32_e32 v3, v1
	v_readlane_b32 s28, v253, 5
	v_readlane_b32 s29, v253, 6
	v_lshl_add_u64 v[114:115], v[4:5], 0, v[2:3]
	v_lshlrev_b32_e32 v2, 17, v6
	v_lshlrev_b32_e32 v128, 9, v6
	ds_read_b32 v244, v128 offset:508
	v_lshl_add_u64 v[116:117], s[28:29], 0, v[0:1]
	s_mov_b64 s[4:5], 0
	v_lshlrev_b32_e32 v129, 1, v2
	v_readlane_b32 s17, v252, 58
	v_readlane_b32 s18, v252, 59
	v_readlane_b32 s19, v252, 60
	v_readlane_b32 s20, v252, 61
	v_readlane_b32 s21, v252, 62
	v_readlane_b32 s22, v252, 63
	v_readlane_b32 s23, v253, 0
	v_readlane_b32 s26, v253, 3
	v_readlane_b32 s27, v253, 4
	v_readlane_b32 s30, v253, 7
	v_readlane_b32 s31, v253, 8
	s_branch .LBB0_318

; template <int MODE> ...
;     ...
;     tmax = fmaxf(tmax, __shfl_xor(tmax, 32));
;     const float m_new = fmaxf(m_run, tmax);
;     if (__ballot(m_new != m_run) != 0ull) {
;       const float alpha = __builtin_amdgcn_exp2f(m_run - m_new);
;       l_run *= alpha; m_run = m_new;
; #pragma unroll
;       for (int e = 0; e < 16; ++e) { oacc[0][e] *= alpha; oacc[1][e] *= alpha; }
;     }
.LBB0_323:
	v_mov_b32_e32 v34, v170
	v_mov_b32_e32 v246, v170
	s_nop 1
	v_permlane32_swap_b32_e32 v34, v246
	v_max3_f32 v34, v152, v34, v246
	v_cmp_neq_f32_e32 vcc, v34, v152
	s_cbranch_vccz .LBB0_330
	v_sub_f32_e32 v35, v152, v34
	v_exp_f32_e32 v36, v35
	v_mov_b32_e32 v152, v34
	v_mul_f32_e32 v132, v132, v36
	v_pk_mul_f32 v[32:33], v[32:33], v[36:37] op_sel_hi:[1,0]
	v_pk_mul_f32 v[30:31], v[30:31], v[36:37] op_sel_hi:[1,0]
	v_pk_mul_f32 v[28:29], v[28:29], v[36:37] op_sel_hi:[1,0]
	v_pk_mul_f32 v[26:27], v[26:27], v[36:37] op_sel_hi:[1,0]
	v_pk_mul_f32 v[24:25], v[24:25], v[36:37] op_sel_hi:[1,0]
	v_pk_mul_f32 v[22:23], v[22:23], v[36:37] op_sel_hi:[1,0]
	v_pk_mul_f32 v[20:21], v[20:21], v[36:37] op_sel_hi:[1,0]
	v_pk_mul_f32 v[18:19], v[18:19], v[36:37] op_sel_hi:[1,0]
	v_pk_mul_f32 v[16:17], v[16:17], v[36:37] op_sel_hi:[1,0]
	v_pk_mul_f32 v[14:15], v[14:15], v[36:37] op_sel_hi:[1,0]
	v_pk_mul_f32 v[12:13], v[12:13], v[36:37] op_sel_hi:[1,0]
	v_pk_mul_f32 v[10:11], v[10:11], v[36:37] op_sel_hi:[1,0]
	v_pk_mul_f32 v[8:9], v[8:9], v[36:37] op_sel_hi:[1,0]
	v_pk_mul_f32 v[6:7], v[6:7], v[36:37] op_sel_hi:[1,0]
	v_pk_mul_f32 v[4:5], v[4:5], v[36:37] op_sel_hi:[1,0]
	v_pk_mul_f32 v[2:3], v[2:3], v[36:37] op_sel_hi:[1,0]

; template <int MODE> ...
;     ...
;     if (far) {
;       const float b127 = lut[127];
;       const unsigned mbs = mb >> (4 * hh);
;       const int dbase = t - key0 - 4 * hh;
; #pragma unroll
;       for (int e = 0; e < 16; ++e) {
;         const int ce = (e & 3) + 8 * (e >> 2);
;         bool ok;
;         if (MODE == 0) ok = (mbs & (1u << ce)) != 0u;
;         else if (MODE == 1) ok = mb != 0u;
;         else ok = (dbase - ce) < 512;
;         const float lg = __builtin_fmaf(s[e], 0.18033688011112042f, b127);
;         pv[e] = ok ? lg : -1e30f;
;         tmax = fmaxf(tmax, pv[e]);
;       }
.LBB0_328:
	s_andn2_b64 vcc, exec, s[0:1]
	s_cbranch_vccnz .LBB0_323
	s_waitcnt vmcnt(9)
	v_lshrrev_b32_e32 v154, v134, v154
	v_and_b32_e32 v153, 2, v154
	v_and_b32_e32 v156, 1, v154
	v_cmp_ne_u32_e32 vcc, 0, v153
	s_waitcnt lgkmcnt(0)
	s_nop 1
	v_pk_fma_f32 v[34:35], v[34:35], s[96:97], v[244:245] op_sel_hi:[1,0,0]
	v_and_b32_e32 v159, 4, v154
	v_cndmask_b32_e32 v155, v235, v35, vcc
	v_cmp_ne_u32_e32 vcc, 0, v156
	v_and_b32_e32 v156, 8, v154
	s_nop 0
	v_cndmask_b32_e32 v153, v235, v34, vcc
	v_pk_fma_f32 v[34:35], v[36:37], s[96:97], v[244:245] op_sel_hi:[1,0,0]
	v_cmp_ne_u32_e32 vcc, 0, v156
	v_max3_f32 v158, v153, s82, v155
	v_and_b32_e32 v37, 0x200, v154
	v_cndmask_b32_e32 v157, v235, v35, vcc
	v_cmp_ne_u32_e32 vcc, 0, v159
	s_nop 1
	v_cndmask_b32_e32 v156, v235, v34, vcc
	v_max3_f32 v36, v158, v156, v157
	v_and_b32_e32 v158, 0x100, v154
	v_pk_fma_f32 v[34:35], v[38:39], s[96:97], v[244:245] op_sel_hi:[1,0,0]
	v_cmp_ne_u32_e32 vcc, 0, v37
	v_and_b32_e32 v37, 0x800, v154
	v_and_b32_e32 v38, 0x400, v154
	v_cndmask_b32_e32 v159, v235, v35, vcc
	v_cmp_ne_u32_e32 vcc, 0, v158
	s_nop 1
	v_cndmask_b32_e32 v158, v235, v34, vcc
	v_pk_fma_f32 v[34:35], v[40:41], s[96:97], v[244:245] op_sel_hi:[1,0,0]
	v_cmp_ne_u32_e32 vcc, 0, v37
	v_and_b32_e32 v37, 0x20000, v154
	v_max3_f32 v36, v36, v158, v159
	v_cndmask_b32_e32 v162, v235, v35, vcc
	v_cmp_ne_u32_e32 vcc, 0, v38
	v_and_b32_e32 v38, 0x10000, v154
	s_nop 0
	v_cndmask_b32_e32 v160, v235, v34, vcc
	v_pk_fma_f32 v[34:35], v[42:43], s[96:97], v[244:245] op_sel_hi:[1,0,0]
	v_cmp_ne_u32_e32 vcc, 0, v37
	v_and_b32_e32 v37, 0x80000, v154
	v_max3_f32 v36, v36, v160, v162
	v_cndmask_b32_e32 v164, v235, v35, vcc
	v_cmp_ne_u32_e32 vcc, 0, v38
	v_and_b32_e32 v38, 0x40000, v154
	s_nop 0
	v_cndmask_b32_e32 v163, v235, v34, vcc
	v_pk_fma_f32 v[34:35], v[44:45], s[96:97], v[244:245] op_sel_hi:[1,0,0]
	v_cmp_ne_u32_e32 vcc, 0, v37
	v_and_b32_e32 v37, 0x2000000, v154
	v_max3_f32 v36, v36, v163, v164
	v_cndmask_b32_e32 v166, v235, v35, vcc
	v_cmp_ne_u32_e32 vcc, 0, v38
	v_and_b32_e32 v38, 0x1000000, v154
	s_nop 0
	v_cndmask_b32_e32 v165, v235, v34, vcc
	v_pk_fma_f32 v[34:35], v[46:47], s[96:97], v[244:245] op_sel_hi:[1,0,0]
	v_cmp_ne_u32_e32 vcc, 0, v37
	v_and_b32_e32 v37, 0x8000000, v154
	v_max3_f32 v36, v36, v165, v166
	v_cndmask_b32_e32 v168, v235, v35, vcc
	v_cmp_ne_u32_e32 vcc, 0, v38
	v_and_b32_e32 v38, 0x4000000, v154
	s_nop 0
	v_cndmask_b32_e32 v167, v235, v34, vcc
	v_pk_fma_f32 v[34:35], v[48:49], s[96:97], v[244:245] op_sel_hi:[1,0,0]
	v_cmp_ne_u32_e32 vcc, 0, v37
	v_max3_f32 v36, v36, v167, v168
	s_nop 0
	v_cndmask_b32_e32 v161, v235, v35, vcc
	v_cmp_ne_u32_e32 vcc, 0, v38
	s_nop 1
	v_cndmask_b32_e32 v169, v235, v34, vcc
	v_max3_f32 v170, v36, v169, v161
	s_branch .LBB0_323
